# convert_ffn item loop: waits on the next item's loads moved behind the current item's transpose/store (finish-block temporaries renamed off the load destinations)
# speedup vs baseline: 1.0136x; 1.0008x over previous
.LBB0_611:
	s_and_b64 s[4:5], s[4:5], exec
	s_movk_i32 s4, 0x400
	s_cselect_b32 s18, s4, 0xb00
	s_mov_b32 s4, 0x1c00000
	v_add_u32_e32 v95, s12, v37
	s_cselect_b32 s4, s4, 0x2700000
	s_add_u32 s4, s36, s4
	v_mad_i64_i32 v[100:101], s[20:21], s18, v95, 0
	ds_read2_b32 v[96:97], v38 offset1:33
	s_addc_u32 s5, s37, 0
	s_lshl_b32 s20, s13, 6
	s_waitcnt lgkmcnt(0)
	v_cvt_pk_bf16_f32 v96, v96, v97
	ds_read2_b32 v[98:99], v38 offset0:66 offset1:99
	s_ashr_i32 s21, s20, 31
	s_waitcnt lgkmcnt(0)
	v_cvt_pk_bf16_f32 v97, v98, v99
	ds_read2_b32 v[98:99], v38 offset0:132 offset1:165
	v_lshl_add_u64 v[100:101], v[100:101], 1, s[4:5]
	s_lshl_b64 s[20:21], s[20:21], 1
	v_mov_b32_e32 v35, v1
	s_waitcnt lgkmcnt(0)
	v_cvt_pk_bf16_f32 v98, v98, v99
	ds_read2_b32 v[102:103], v38 offset0:198 offset1:231
	v_lshl_add_u64 v[100:101], v[100:101], 0, s[20:21]
	s_waitcnt lgkmcnt(0)
	v_cvt_pk_bf16_f32 v99, v102, v103
	ds_read2_b32 v[102:103], v38 offset0:8 offset1:41
	v_lshl_add_u64 v[100:101], v[100:101], 0, v[34:35]
	v_add_u32_e32 v95, s12, v39
	global_store_dwordx4 v[100:101], v[96:99], off
	s_andn2_b64 vcc, exec, s[10:11]
	s_waitcnt lgkmcnt(0)
	v_cvt_pk_bf16_f32 v96, v102, v103
	v_mad_i64_i32 v[102:103], s[22:23], s18, v95, 0
	v_lshl_add_u64 v[102:103], v[102:103], 1, s[4:5]
	ds_read2_b32 v[98:99], v38 offset0:74 offset1:107
	v_lshl_add_u64 v[102:103], v[102:103], 0, s[20:21]
	s_waitcnt lgkmcnt(0)
	v_cvt_pk_bf16_f32 v97, v98, v99
	ds_read2_b32 v[98:99], v38 offset0:140 offset1:173
	v_lshl_add_u64 v[102:103], v[102:103], 0, v[34:35]
	v_add_u32_e32 v95, s12, v40
	s_waitcnt lgkmcnt(0)
	v_cvt_pk_bf16_f32 v98, v98, v99
	ds_read2_b32 v[100:101], v38 offset0:206 offset1:239
	s_waitcnt lgkmcnt(0)
	v_cvt_pk_bf16_f32 v99, v100, v101
	global_store_dwordx4 v[102:103], v[96:99], off
	v_mad_i64_i32 v[102:103], s[22:23], s18, v95, 0
	v_lshl_add_u64 v[102:103], v[102:103], 1, s[4:5]
	ds_read2_b32 v[100:101], v38 offset0:16 offset1:49
	s_waitcnt lgkmcnt(0)
	v_cvt_pk_bf16_f32 v96, v100, v101
	ds_read2_b32 v[98:99], v38 offset0:82 offset1:115
	v_lshl_add_u64 v[102:103], v[102:103], 0, s[20:21]
	s_waitcnt lgkmcnt(0)
	v_cvt_pk_bf16_f32 v97, v98, v99
	ds_read2_b32 v[98:99], v38 offset0:148 offset1:181
	v_lshl_add_u64 v[102:103], v[102:103], 0, v[34:35]
	v_add_u32_e32 v95, s12, v41
	s_waitcnt lgkmcnt(0)
	v_cvt_pk_bf16_f32 v98, v98, v99
	ds_read2_b32 v[100:101], v38 offset0:214 offset1:247
	s_waitcnt lgkmcnt(0)
	v_cvt_pk_bf16_f32 v99, v100, v101
	global_store_dwordx4 v[102:103], v[96:99], off
	v_mad_i64_i32 v[102:103], s[12:13], s18, v95, 0
	v_lshl_add_u64 v[102:103], v[102:103], 1, s[4:5]
	ds_read2_b32 v[100:101], v38 offset0:24 offset1:57
	s_waitcnt lgkmcnt(0)
	v_cvt_pk_bf16_f32 v96, v100, v101
	ds_read2_b32 v[98:99], v38 offset0:90 offset1:123
	v_lshl_add_u64 v[102:103], v[102:103], 0, s[20:21]
	s_waitcnt lgkmcnt(0)
	v_cvt_pk_bf16_f32 v97, v98, v99
	ds_read2_b32 v[98:99], v38 offset0:156 offset1:189
	v_lshl_add_u64 v[102:103], v[102:103], 0, v[34:35]
	s_waitcnt lgkmcnt(0)
	v_cvt_pk_bf16_f32 v98, v98, v99
	ds_read2_b32 v[100:101], v38 offset0:222 offset1:255
	s_waitcnt lgkmcnt(0)
	v_cvt_pk_bf16_f32 v99, v100, v101
	global_store_dwordx4 v[102:103], v[96:99], off
	s_waitcnt lgkmcnt(0)
	s_waitcnt vmcnt(35)
	v_mul_f32_e32 v2, v3, v9
	s_waitcnt vmcnt(34)
	v_mul_f32_e32 v3, v8, v10
	s_waitcnt vmcnt(33)
	v_mul_f32_e32 v4, v12, v13
	s_waitcnt vmcnt(32)
	v_mul_f32_e32 v5, v11, v14
	s_waitcnt vmcnt(31)
	v_mul_f32_e32 v6, v16, v17
	s_waitcnt vmcnt(30)
	v_mul_f32_e32 v7, v15, v18
	s_waitcnt vmcnt(29)
	v_mul_f32_e32 v8, v20, v21
	s_waitcnt vmcnt(28)
	v_mul_f32_e32 v9, v19, v22
	s_waitcnt vmcnt(27)
	v_mul_f32_e32 v10, v24, v25
	s_waitcnt vmcnt(26)
	v_mul_f32_e32 v11, v23, v26
	s_waitcnt vmcnt(25)
	v_mul_f32_e32 v12, v28, v29
	s_waitcnt vmcnt(24)
	v_mul_f32_e32 v13, v27, v30
	s_waitcnt vmcnt(23)
	v_mul_f32_e32 v14, v32, v33
	s_waitcnt vmcnt(22)
	v_mul_f32_e32 v15, v31, v94
	s_waitcnt vmcnt(21)
	v_mul_f32_e32 v16, v44, v45
	s_waitcnt vmcnt(20)
	v_mul_f32_e32 v17, v43, v46
	s_waitcnt vmcnt(19)
	v_mul_f32_e32 v18, v48, v49
	s_waitcnt vmcnt(18)
	v_mul_f32_e32 v19, v47, v50
	s_waitcnt vmcnt(17)
	v_mul_f32_e32 v20, v52, v53
	s_waitcnt vmcnt(16)
	v_mul_f32_e32 v21, v51, v54
	s_waitcnt vmcnt(15)
	v_mul_f32_e32 v22, v56, v57
	s_waitcnt vmcnt(14)
	v_mul_f32_e32 v23, v55, v58
	s_waitcnt vmcnt(13)
	v_mul_f32_e32 v24, v60, v61
	s_waitcnt vmcnt(12)
	v_mul_f32_e32 v25, v59, v62
	s_waitcnt vmcnt(11)
	v_mul_f32_e32 v26, v64, v65
	s_waitcnt vmcnt(10)
	v_mul_f32_e32 v27, v63, v66
	s_waitcnt vmcnt(9)
	v_mul_f32_e32 v28, v68, v69
	s_waitcnt vmcnt(8)
	v_mul_f32_e32 v29, v67, v70
	s_waitcnt vmcnt(7)
	v_mul_f32_e32 v30, v72, v73
	s_waitcnt vmcnt(6)
	v_mul_f32_e32 v31, v71, v75
	s_waitcnt vmcnt(5)
	v_mul_f32_e32 v32, v76, v77
	s_waitcnt vmcnt(4)
	v_mul_f32_e32 v33, v74, v78
	s_mov_b32 s18, s19
	s_cbranch_vccz .Lmy_cvf_end

.LBB0_641:
	v_or_b32_e32 v35, 26, v2
	v_mad_i64_i32 v[44:45], s[12:13], v35, s20, 0
	v_lshl_add_u64 v[44:45], v[44:45], 2, v[4:5]
	global_load_dword v94, v[44:45], off nt
	v_mov_b32_e32 v43, 1.0
	s_and_b64 vcc, exec, s[4:5]
	v_mov_b32_e32 v44, 1.0
	s_cbranch_vccnz .LBB0_643
	global_load_dword v44, v[6:7], off offset:112

.LBB0_677:
	v_or_b32_e32 v2, 62, v2
	v_mad_i64_i32 v[6:7], s[4:5], v2, s20, 0
	v_lshl_add_u64 v[4:5], v[6:7], 2, v[4:5]
	global_load_dword v78, v[4:5], off
.LBB0_678:
	s_cmpk_lt_i32 s18, 0xb00
	s_cselect_b64 s[4:5], -1, 0
	s_and_b64 s[12:13], s[4:5], exec
	s_cselect_b32 s12, 0xb0, 32
	v_cvt_f32_ubyte0_e32 v35, s12
	v_rcp_iflag_f32_e32 v35, v35
	s_cselect_b32 s13, 0, 0xfffff500
	s_add_i32 s20, s13, s18
	s_sub_i32 s13, 0, s12
	v_mul_f32_e32 v35, 0x4f7ffffe, v35
	v_cvt_u32_f32_e32 v35, v35
	s_abs_i32 s22, s20
	s_ashr_i32 s21, s20, 31
	s_waitcnt lgkmcnt(0)
	v_readfirstlane_b32 s23, v35
	s_mul_i32 s13, s13, s23
	s_mul_hi_u32 s13, s23, s13
	s_add_i32 s23, s23, s13
	s_mul_hi_u32 s13, s22, s23
	s_mul_i32 s23, s13, s12
	s_sub_i32 s22, s22, s23
	s_add_i32 s24, s13, 1
	s_sub_i32 s23, s22, s12
	s_cmp_ge_u32 s22, s12
	s_cselect_b32 s13, s24, s13
	s_cselect_b32 s22, s23, s22
	s_add_i32 s23, s13, 1
	s_cmp_ge_u32 s22, s12
	s_cselect_b32 s13, s23, s13
	s_xor_b32 s13, s13, s21
	s_sub_i32 s13, s13, s21
	s_mul_i32 s12, s13, s12
	s_sub_i32 s20, s20, s12
	s_lshl_b32 s12, s20, 5
	s_cmpk_gt_i32 s18, 0xaff
	s_cbranch_scc1 .LBB0_611
	s_add_i32 s18, s12, 0xfffff500
	s_cmpk_lt_i32 s20, 0x58
	s_cselect_b32 s12, s12, s18
	s_cselect_b32 s18, 0, 0x80
	s_lshl_b32 s20, s12, 1
	s_and_b32 s12, s12, 0x60
	s_and_b32 s20, s20, 0xffffff00
	s_or_b32 s12, s12, s18
	s_or_b32 s12, s12, s20
	s_branch .LBB0_611
